# speedup vs baseline: 1.0885x; 1.0236x over previous
; __global__ void __launch_bounds__(512, 2) mega_kernel(Params p) {
;     ...
;   cg::grid_group grid = cg::this_grid();
;   phase0(p, smem);
;   asm volatile("s_waitcnt vmcnt(0) lgkmcnt(0)" ::: "memory");
;   __syncthreads();
;   grid.sync();
;   int sweep = 0;
;   for (int layer = 0; layer < 4; ++layer) {
;     const bool odd = (layer & 1) != 0;
;     const int li = layer >> 1;
;     const int nsteps = odd ? 8 : 5;
;     for (int st = 0; st < nsteps; ++st) {
.LBB0_159:
	s_or_b64 exec, exec, s[0:1]
	s_mov_b64 s[4:5], exec
	s_and_b64 exec, exec, s[94:95]
	s_getreg_b32 s2, hwreg(HW_REG_XCC_ID, 0, 4)
	s_lshl_b32 s6, s2, 8
	s_add_u32 s2, s78, 0x6008000
	s_addc_u32 s3, s79, 0
	v_mov_b32_e32 v0, s6
	v_mov_b32_e32 v1, 1
	global_atomic_add v0, v1, s[2:3] offset:256
	s_mov_b64 exec, s[4:5]
	s_mov_b32 s99, 0
	s_mov_b32 s100, 0
	s_add_u32 s0, s78, 0xe981000
	s_addc_u32 s1, s79, 0
	v_writelane_b32 v252, s0, 51
	s_mov_b64 s[8:9], s[68:69]
	s_mov_b64 s[16:17], s[76:77]
	v_writelane_b32 v252, s1, 52
	s_add_u32 s0, s78, 0x6981000
	s_addc_u32 s1, s79, 0
	v_writelane_b32 v252, s0, 53
	s_mov_b64 s[10:11], s[70:71]
	s_mov_b64 s[12:13], s[72:73]
	v_writelane_b32 v252, s1, 54
	s_add_u32 s0, s78, 0x34181000
	s_addc_u32 s1, s79, 0
	v_writelane_b32 v252, s0, 55
	s_mov_b64 s[18:19], s[78:79]
	s_mov_b64 s[6:7], s[66:67]
	v_writelane_b32 v252, s1, 56
	s_add_u32 s0, s78, 0x33981000
	s_addc_u32 s1, s79, 0
	v_writelane_b32 v252, s0, 57
	s_movk_i32 s90, 0x100
	s_mov_b32 s44, 0x10000
	v_writelane_b32 v252, s1, 58
	s_add_u32 s0, s78, 0x30981000
	s_addc_u32 s1, s79, 0
	v_writelane_b32 v252, s0, 59
	s_movk_i32 s33, 0x2000
	s_movk_i32 s58, 0x4000
	v_writelane_b32 v252, s1, 60
	s_add_u32 s0, s78, 0x6080000
	v_writelane_b32 v252, s0, 61
	s_addc_u32 s0, s79, 0
	v_writelane_b32 v252, s0, 62
	s_add_u32 s0, s78, 0x24981000
	s_addc_u32 s1, s79, 0
	v_writelane_b32 v252, s0, 63
	s_movk_i32 s41, 0x1000
	v_readlane_b32 s2, v252, 34
	v_writelane_b32 v253, s1, 0
	s_ashr_i32 s0, s2, 31
	s_lshr_b32 s0, s0, 29
	s_add_i32 s0, s2, s0
	s_ashr_i32 s1, s0, 3
	s_and_b32 s0, s0, -8
	s_sub_i32 s0, s2, s0
	v_writelane_b32 v253, s1, 1
	s_cmp_lt_i32 s0, 0
	v_writelane_b32 v253, s0, 2
	s_cselect_b64 s[0:1], -1, 0
	v_writelane_b32 v253, s0, 3
	s_cmpk_lt_i32 s2, 0x100
	s_mov_b32 s71, 0x800000
	v_writelane_b32 v253, s1, 4
	s_cselect_b64 s[0:1], -1, 0
	v_writelane_b32 v253, s0, 5
	v_mov_b32_e32 v153, 0
	s_mov_b32 s59, 0xe989000
	v_writelane_b32 v253, s1, 6
	s_add_u32 s0, s78, 0x2c981000
	s_addc_u32 s1, s79, 0
	v_writelane_b32 v253, s0, 7
	s_mov_b32 s70, 0xe98a000
	s_mov_b32 s54, 0xe98b000
	v_writelane_b32 v253, s1, 8
	s_add_u32 s0, s78, 0x6101000
	s_addc_u32 s1, s79, 0
	v_writelane_b32 v253, s0, 9
	s_mov_b32 s55, 0xe98c000
	s_mov_b32 s66, 0xe98d000
	v_writelane_b32 v253, s1, 10
	s_add_u32 s0, s78, 0x6081000
	s_addc_u32 s1, s79, 0
	v_writelane_b32 v253, s0, 11
	s_mov_b32 s67, 0xe98e000
	s_mov_b32 s91, 0xe98f000
	v_writelane_b32 v253, s1, 12
	s_mul_i32 s0, s2, 9
	s_addk_i32 s0, 0xff00
	s_cmpk_lt_i32 s2, 0x800
	s_cselect_b64 s[4:5], -1, 0
	s_cmp_lt_i32 s2, 64
	s_mul_i32 s1, s2, 5
	v_writelane_b32 v253, s4, 13
	s_cselect_b32 s0, s1, s0
	s_cselect_b32 s1, 5, 9
	s_cmpk_eq_i32 s45, 0x100
	v_writelane_b32 v253, s5, 14
	s_cselect_b32 s0, s0, s2
	s_cselect_b32 s1, s1, 0x800
	v_writelane_b32 v253, s1, 15
	s_cselect_b32 s1, 1, s45
	s_cmpk_lt_i32 s0, 0x800
	v_writelane_b32 v253, s0, 16
	s_cselect_b64 s[4:5], -1, 0
	v_writelane_b32 v253, s4, 17
	s_cmp_eq_u32 s1, 1
	s_mov_b32 s65, 0xe990000
	v_writelane_b32 v253, s5, 18
	v_writelane_b32 v253, s1, 19
	s_cselect_b64 s[0:1], -1, 0
	v_writelane_b32 v253, s0, 20
	s_mov_b32 s46, 0x24981000
	s_mov_b32 s47, 0x24982000
	v_writelane_b32 v253, s1, 21
	v_writelane_b32 v253, s4, 22
	s_add_u32 s0, s78, 0xe980c00
	s_addc_u32 s1, s79, 0
	v_writelane_b32 v253, s5, 23
	v_writelane_b32 v253, s6, 24
	v_writelane_b32 v253, s7, 25
	v_writelane_b32 v253, s8, 26
	v_writelane_b32 v253, s9, 27
	v_writelane_b32 v253, s10, 28
	v_writelane_b32 v253, s11, 29
	v_writelane_b32 v253, s12, 30
	v_writelane_b32 v253, s13, 31
	v_writelane_b32 v253, s14, 32
	v_writelane_b32 v253, s15, 33
	v_writelane_b32 v253, s16, 34
	v_writelane_b32 v253, s17, 35
	v_writelane_b32 v253, s18, 36
	v_writelane_b32 v253, s19, 37
	v_writelane_b32 v253, s0, 38
	s_mov_b32 s92, 0x24983000
	s_mov_b32 s93, 0x24984000
	v_writelane_b32 v253, s1, 39
	s_lshl_b32 s0, s45, 4
	v_writelane_b32 v253, s0, 40
	s_lshl_b32 s0, s45, 9
	v_writelane_b32 v253, s0, 41
	s_lshl_b32 s0, s2, 8
	v_writelane_b32 v253, s0, 42
	s_lshl_b32 s0, s45, 8
	v_writelane_b32 v253, s0, 43
	s_mov_b32 s1, 0
	v_writelane_b32 v253, s0, 44
	v_mov_b32_e32 v154, 0x358637bd
	v_mov_b32_e32 v210, 1
	v_writelane_b32 v253, s1, 45
	v_writelane_b32 v253, s94, 46
	v_mbcnt_hi_u32_b32 v211, -1, v46
	v_mov_b32_e32 v212, 0x1a000
	v_writelane_b32 v253, s95, 47
	v_writelane_b32 v253, s89, 48
	v_mov_b32_e32 v213, 0x461c4000
	v_mov_b32_e32 v214, 0xff61b1e6
	v_mov_b32_e32 v215, 0x7f61b1e6
	v_mov_b32_e32 v216, 0x300
	v_mov_b32_e32 v217, 0x1400
	s_movk_i32 s52, 0x200
	s_movk_i32 s53, 0x1400
	s_movk_i32 s64, 0x300
	s_movk_i32 s39, 0x400
	s_movk_i32 s40, 0x4600
	s_mov_b32 s48, 0x5040100
	s_mov_b32 s49, 0xff61b1e6
	s_mov_b32 s69, 0
	s_mov_b32 s6, 0
	v_writelane_b32 v253, s88, 49
	s_barrier
	s_branch .LBB0_161

; __global__ void __launch_bounds__(512, 2) mega_kernel(Params p) {
;     ...
;       asm volatile("s_waitcnt vmcnt(0) lgkmcnt(0)" ::: "memory");
;       __syncthreads();
;       if (!(odd && st == 2)) grid.sync();
.LBB0_579:
	s_waitcnt vmcnt(0) lgkmcnt(0)
	s_andn2_b64 vcc, exec, s[50:51]
	s_waitcnt lgkmcnt(0)
	s_barrier
	s_cbranch_vccnz .LBB0_164
	s_barrier
	s_and_saveexec_b64 s[0:1], s[94:95]
	s_cbranch_execz .LBB0_163
	v_readlane_b32 s2, v252, 0
	v_readlane_b32 s3, v252, 1
	s_load_dword s6, s[2:3], 0x0
	s_sub_u32 s2, s2, 8
	s_subb_u32 s3, s3, 0
	s_load_dwordx2 s[4:5], s[2:3], 0x0
	s_getreg_b32 s7, hwreg(HW_REG_XCC_ID, 0, 4)
	s_waitcnt lgkmcnt(0)
	s_add_u32 s2, s4, 0x6008000
	s_addc_u32 s3, s5, 0
	s_lshl_b32 s8, s7, 8
	s_cmp_lg_u32 s99, 0
	s_cbranch_scc1 .Lxb_have
.Lxb_census:
	s_mov_b64 s[4:5], exec
	s_mov_b32 exec_lo, 0xffff
	s_mov_b32 exec_hi, 0
	v_lshlrev_b32_e32 v0, 8, v211
	global_load_dword v1, v0, s[2:3] offset:256 sc1
	s_waitcnt vmcnt(0)
	v_cmp_ne_u32_e32 vcc, 0, v1
	s_bcnt1_i32_b64 s100, vcc
	s_nop 1
	v_add_u32_dpp v2, v1, v1 quad_perm:[1,0,3,2] row_mask:0xf bank_mask:0xf
	s_nop 1
	v_add_u32_dpp v2, v2, v2 quad_perm:[2,3,0,1] row_mask:0xf bank_mask:0xf
	s_nop 1
	v_add_u32_dpp v2, v2, v2 row_half_mirror row_mask:0xf bank_mask:0xf
	s_nop 1
	v_add_u32_dpp v2, v2, v2 row_mirror row_mask:0xf bank_mask:0xf
	s_nop 0
	v_readfirstlane_b32 s9, v2
	v_readlane_b32 s99, v1, s7
	s_mov_b64 exec, s[4:5]
	s_cmp_eq_u32 s9, s6
	s_cbranch_scc1 .Lxb_have
	s_sleep 4
	s_branch .Lxb_census
.Lxb_have:
	s_add_u32 s9, s8, 0x1100
	v_mov_b32_e32 v0, s9
	v_mov_b32_e32 v2, 1
	global_atomic_add v2, v0, v2, s[2:3] sc0
	s_waitcnt vmcnt(0)
	v_readfirstlane_b32 s4, v2
	s_and_b32 s5, s4, 0xffff
	s_lshr_b32 s4, s4, 16
	s_add_i32 s9, s99, -1
	s_cmp_eq_u32 s5, s9
	s_cbranch_scc1 .Lxb_leader
	s_add_u32 s9, s8, 0x2100
	v_mov_b32_e32 v0, s9
.Lxb_poll_loc:
	global_load_dword v1, v0, s[2:3] sc1
	s_waitcnt vmcnt(0)
	v_readfirstlane_b32 s5, v1
	s_and_b32 s5, s5, 0xffff
	s_cmp_lg_u32 s5, s4
	s_cbranch_scc1 .LBB0_162
	s_sleep 1
	s_branch .Lxb_poll_loc
.Lxb_leader:
	s_sub_u32 s5, 0x10000, s99
	v_mov_b32_e32 v1, s5
	global_atomic_add v0, v1, s[2:3]
	buffer_wbl2 sc1
	s_waitcnt vmcnt(0)
	v_mov_b32_e32 v0, 0x3100
	v_mov_b32_e32 v2, 1
	global_atomic_add v2, v0, v2, s[2:3] sc0
	s_waitcnt vmcnt(0)
	v_readfirstlane_b32 s5, v2
	s_and_b32 s6, s5, 0xffff
	s_lshr_b32 s5, s5, 16
	s_add_i32 s9, s100, -1
	s_cmp_eq_u32 s6, s9
	s_cbranch_scc0 .Lxb_poll_top
	s_sub_u32 s6, 0x10000, s100
	v_mov_b32_e32 v1, s6
	global_atomic_add v0, v1, s[2:3]
	s_waitcnt vmcnt(0)
	v_mov_b32_e32 v0, 0x3200
	v_mov_b32_e32 v1, 1
	global_atomic_add v0, v1, s[2:3]
	s_branch .Lxb_release
.Lxb_poll_top:
	v_mov_b32_e32 v0, 0x3200
.Lxb_poll_top2:
	global_load_dword v1, v0, s[2:3] sc1
	s_waitcnt vmcnt(0)
	v_readfirstlane_b32 s6, v1
	s_and_b32 s6, s6, 0xffff
	s_cmp_lg_u32 s6, s5
	s_cbranch_scc1 .Lxb_release
	s_sleep 1
	s_branch .Lxb_poll_top2
.Lxb_release:
	buffer_inv sc1
	s_add_u32 s9, s8, 0x2100
	v_mov_b32_e32 v0, s9
	v_mov_b32_e32 v1, 1
	global_atomic_add v0, v1, s[2:3]
	s_waitcnt vmcnt(0)
	s_branch .LBB0_163

; __global__ void __launch_bounds__(512, 2) mega_kernel(Params p) {
;   __shared__ __attribute__((aligned(16))) char smem[131072];
	.amdhsa_kernel _Z11mega_kernel6Params
		.amdhsa_group_segment_fixed_size 131072
		.amdhsa_private_segment_fixed_size 0
		.amdhsa_kernarg_size 448
		.amdhsa_user_sgpr_count 2
		.amdhsa_user_sgpr_dispatch_ptr 0
		.amdhsa_user_sgpr_queue_ptr 0
		.amdhsa_user_sgpr_kernarg_segment_ptr 1
		.amdhsa_user_sgpr_dispatch_id 0
		.amdhsa_user_sgpr_kernarg_preload_length 0
		.amdhsa_user_sgpr_kernarg_preload_offset 0
		.amdhsa_user_sgpr_private_segment_size 0
		.amdhsa_uses_dynamic_stack 0
		.amdhsa_enable_private_segment 0
		.amdhsa_system_sgpr_workgroup_id_x 1
		.amdhsa_system_sgpr_workgroup_id_y 0
		.amdhsa_system_sgpr_workgroup_id_z 0
		.amdhsa_system_sgpr_workgroup_info 0
		.amdhsa_system_vgpr_workitem_id 2
		.amdhsa_next_free_vgpr 254
		.amdhsa_next_free_sgpr 102
		.amdhsa_accum_offset 256
		.amdhsa_reserve_vcc 1
		.amdhsa_float_round_mode_32 0
		.amdhsa_float_round_mode_16_64 0
		.amdhsa_float_denorm_mode_32 3
		.amdhsa_float_denorm_mode_16_64 3
		.amdhsa_dx10_clamp 1
		.amdhsa_ieee_mode 1
		.amdhsa_fp16_overflow 0
		.amdhsa_tg_split 0
		.amdhsa_exception_fp_ieee_invalid_op 0
		.amdhsa_exception_fp_denorm_src 0
		.amdhsa_exception_fp_ieee_div_zero 0
		.amdhsa_exception_fp_ieee_overflow 0
		.amdhsa_exception_fp_ieee_underflow 0
		.amdhsa_exception_fp_ieee_inexact 0
		.amdhsa_exception_int_div_zero 0
	.end_amdhsa_kernel

; __global__ void __launch_bounds__(512, 2) mega_kernel(Params p) {
;   __shared__ __attribute__((aligned(16))) char smem[131072];
amdhsa.kernels:
  - .agpr_count:     0
    .args:
      - .offset:         0
        .size:           192
        .value_kind:     by_value
      - .offset:         192
        .size:           4
        .value_kind:     hidden_block_count_x
      - .offset:         196
        .size:           4
        .value_kind:     hidden_block_count_y
      - .offset:         200
        .size:           4
        .value_kind:     hidden_block_count_z
      - .offset:         204
        .size:           2
        .value_kind:     hidden_group_size_x
      - .offset:         206
        .size:           2
        .value_kind:     hidden_group_size_y
      - .offset:         208
        .size:           2
        .value_kind:     hidden_group_size_z
      - .offset:         210
        .size:           2
        .value_kind:     hidden_remainder_x
      - .offset:         212
        .size:           2
        .value_kind:     hidden_remainder_y
      - .offset:         214
        .size:           2
        .value_kind:     hidden_remainder_z
      - .offset:         232
        .size:           8
        .value_kind:     hidden_global_offset_x
      - .offset:         240
        .size:           8
        .value_kind:     hidden_global_offset_y
      - .offset:         248
        .size:           8
        .value_kind:     hidden_global_offset_z
      - .offset:         256
        .size:           2
        .value_kind:     hidden_grid_dims
      - .offset:         280
        .size:           8
        .value_kind:     hidden_multigrid_sync_arg
    .group_segment_fixed_size: 131072
    .kernarg_segment_align: 8
    .kernarg_segment_size: 448
    .language:       OpenCL C
    .language_version:
      - 2
      - 0
    .max_flat_workgroup_size: 512
    .name:           _Z11mega_kernel6Params
    .private_segment_fixed_size: 0
    .sgpr_count:     108
    .sgpr_spill_count: 377
    .symbol:         _Z11mega_kernel6Params.kd
    .uniform_work_group_size: 1
    .uses_dynamic_stack: false
    .vgpr_count:     254
    .vgpr_spill_count: 0
    .wavefront_size: 64
